# UP phase shared-rotary-key epilogue: 16 dependent rope-table load round trips de-serialised (10 distinct loads issued up front, one wait)
# baseline (speedup 1.0000x reference)
; #define LAS __attribute__((address_space(3)))
; __global__ void __launch_bounds__(512, 2) mk_fwd(Args args) {
;     ...
;             if ((int)blockIdx.x >= G - 64) {
;                 const bf16_t* Wkr = WB + WE_IN + (size_t)NKR * DM; const int l15 = lane & 15, l4 = lane >> 4;
;                 const int r0 = 64 * 256 + ((int)blockIdx.x - (G - 64)) * 16; const bf16_t* ap = XM + (size_t)(r0 + l15) * DM + wave * 256 + l4 * 8; const bf16_t* bp = Wkr + (size_t)l15 * DM + wave * 256 + l4 * 8;
;                 f32x4 acc[4] = {{0.f, 0.f, 0.f, 0.f}, {0.f, 0.f, 0.f, 0.f}, {0.f, 0.f, 0.f, 0.f}, {0.f, 0.f, 0.f, 0.f}};
; #pragma unroll
;                 for (int kh = 0; kh < 2; ++kh) {
;                     bf16x8 a[4], bb[4][4];
; #pragma unroll
;                     for (int k = 0; k < 4; ++k) { a[k] = *(const bf16x8*)(ap + (kh * 4 + k) * 32);
; #pragma unroll
;                         for (int nt = 0; nt < 4; ++nt) bb[k][nt] = *(const bf16x8*)(bp + (size_t)nt * 16 * DM + (kh * 4 + k) * 32); }
;                     __builtin_amdgcn_sched_barrier(0);
; #pragma unroll
;                     for (int k = 0; k < 4; ++k)
; #pragma unroll
;                         for (int nt = 0; nt < 4; ++nt) acc[nt] = __builtin_amdgcn_mfma_f32_16x16x32_bf16(a[k], bb[k][nt], acc[nt], 0, 0, 0);
;                     __builtin_amdgcn_sched_barrier(0);
;                 }
;                 LAS f32x4* red = (LAS f32x4*)lds;
; #pragma unroll
;                 for (int nt = 0; nt < 4; ++nt) red[(wave * 4 + nt) * 64 + lane] = acc[nt];
;                 __syncthreads();
.LBB0_523:
	s_andn2_b64 vcc, exec, s[4:5]
	s_cbranch_vccnz .LBB0_662
	v_mov_b32_e32 v147, v0
	s_mov_b32 s4, s31
	s_ashr_i32 s5, s4, 31
	v_readfirstlane_b32 s1, v147
	s_ashr_i32 s0, s1, 6
	s_lshl_b64 s[4:5], s[4:5], 3
	s_waitcnt lgkmcnt(0)
	s_add_u32 s10, s90, s4
	s_addc_u32 s11, s91, s5
	s_load_dwordx2 s[8:9], s[10:11], 0xd0
	v_readlane_b32 s4, v254, 20
	v_bfe_u32 v2, v147, 4, 2
	v_readlane_b32 s5, v254, 21
	s_waitcnt lgkmcnt(0)
	v_and_b32_e32 v159, 15, v147
	s_add_u32 s12, s8, 0x1f4400
	s_addc_u32 s13, s9, 0
	s_add_u32 s16, s8, 0x325a0000
	s_addc_u32 s17, s9, 0
	v_lshlrev_b32_e32 v193, 3, v2
	s_andn2_b64 vcc, exec, s[4:5]
	v_lshlrev_b32_e32 v146, 2, v2
	s_cbranch_vccnz .LBB0_560
	s_lshl_b32 s4, s0, 8
	s_ashr_i32 s5, s4, 31
	v_lshlrev_b32_e32 v178, 12, v159
	s_lshl_b64 s[4:5], s[4:5], 1
	v_lshl_add_u64 v[2:3], s[8:9], 0, v[178:179]
	v_lshl_add_u64 v[2:3], v[2:3], 0, s[4:5]
	v_lshlrev_b32_e32 v178, 1, v193
	v_lshl_add_u64 v[2:3], v[2:3], 0, v[178:179]
	s_mov_b64 s[6:7], 0x3200000
	v_lshl_add_u64 v[12:13], v[2:3], 0, s[6:7]
	v_readlane_b32 s6, v254, 22
	v_mov_b32_e32 v5, v179
	s_cmp_gt_u32 s1, 63
	v_or_b32_e32 v4, s6, v159
	v_lshlrev_b64 v[4:5], 12, v[4:5]
	v_lshl_add_u64 v[4:5], s[8:9], 0, v[4:5]
	v_lshl_add_u64 v[4:5], v[4:5], 0, s[4:5]
	v_lshl_add_u64 v[4:5], v[4:5], 0, v[178:179]
	s_mov_b64 s[4:5], 0x11480000
	v_lshl_add_u64 v[88:89], v[4:5], 0, s[4:5]
	s_mov_b32 s4, 0x11480000
	v_add_co_u32_e32 v4, vcc, s4, v4
	s_mov_b32 s4, 0x3200000
	s_nop 0
	v_addc_co_u32_e32 v5, vcc, 0, v5, vcc
	v_add_co_u32_e32 v8, vcc, s4, v2
	s_mov_b32 s4, 0x3210000
	s_nop 0
	v_addc_co_u32_e32 v9, vcc, 0, v3, vcc
	v_add_co_u32_e32 v90, vcc, s4, v2
	s_mov_b32 s4, 0x3220000
	s_nop 0
	v_addc_co_u32_e32 v91, vcc, 0, v3, vcc
	v_add_co_u32_e32 v92, vcc, s4, v2
	s_mov_b32 s4, 0x3230000
	s_nop 0
	v_addc_co_u32_e32 v93, vcc, 0, v3, vcc
	v_add_co_u32_e32 v100, vcc, s4, v2
	global_load_dwordx4 v[4:7], v[4:5], off
	s_nop 0
	global_load_dwordx4 v[8:11], v[8:9], off
	v_addc_co_u32_e32 v101, vcc, 0, v3, vcc
	global_load_dwordx4 v[16:19], v[90:91], off
	global_load_dwordx4 v[20:23], v[90:91], off offset:64
	global_load_dwordx4 v[24:27], v[92:93], off
	global_load_dwordx4 v[28:31], v[92:93], off offset:64
	global_load_dwordx4 v[32:35], v[100:101], off
	global_load_dwordx4 v[36:39], v[100:101], off offset:64
	global_load_dwordx4 v[40:43], v[12:13], off offset:64
	global_load_dwordx4 v[44:47], v[12:13], off offset:128
	global_load_dwordx4 v[48:51], v[88:89], off offset:128
	global_load_dwordx4 v[52:55], v[88:89], off offset:192
	global_load_dwordx4 v[56:59], v[88:89], off offset:64
	global_load_dwordx4 v[60:63], v[12:13], off offset:192
	global_load_dwordx4 v[64:67], v[90:91], off offset:128
	global_load_dwordx4 v[68:71], v[90:91], off offset:192
	global_load_dwordx4 v[72:75], v[92:93], off offset:128
	global_load_dwordx4 v[76:79], v[92:93], off offset:192
	global_load_dwordx4 v[80:83], v[100:101], off offset:128
	global_load_dwordx4 v[84:87], v[100:101], off offset:192
	v_and_b32_e32 v2, 63, v147
	v_lshl_add_u32 v14, v2, 4, 0
	v_lshl_add_u32 v3, s0, 12, v14
	s_waitcnt vmcnt(0)
	v_mfma_f32_16x16x32_bf16 v[8:11], v[4:7], v[8:11], 0
	v_mfma_f32_16x16x32_bf16 v[16:19], v[4:7], v[16:19], 0
	v_mfma_f32_16x16x32_bf16 v[24:27], v[4:7], v[24:27], 0
	v_mfma_f32_16x16x32_bf16 v[4:7], v[4:7], v[32:35], 0
	v_mfma_f32_16x16x32_bf16 v[8:11], v[56:59], v[40:43], v[8:11]
	v_mfma_f32_16x16x32_bf16 v[16:19], v[56:59], v[20:23], v[16:19]
	v_mfma_f32_16x16x32_bf16 v[20:23], v[56:59], v[28:31], v[24:27]
	v_mfma_f32_16x16x32_bf16 v[4:7], v[56:59], v[36:39], v[4:7]
	v_mfma_f32_16x16x32_bf16 v[8:11], v[48:51], v[44:47], v[8:11]
	v_mfma_f32_16x16x32_bf16 v[16:19], v[48:51], v[64:67], v[16:19]
	v_mfma_f32_16x16x32_bf16 v[20:23], v[48:51], v[72:75], v[20:23]
	v_mfma_f32_16x16x32_bf16 v[4:7], v[48:51], v[80:83], v[4:7]
	v_mfma_f32_16x16x32_bf16 v[8:11], v[52:55], v[60:63], v[8:11]
	v_mfma_f32_16x16x32_bf16 v[16:19], v[52:55], v[68:71], v[16:19]
	v_mfma_f32_16x16x32_bf16 v[20:23], v[52:55], v[76:79], v[20:23]
	v_mfma_f32_16x16x32_bf16 v[4:7], v[52:55], v[84:87], v[4:7]
	global_load_dwordx4 v[24:27], v[88:89], off offset:256
	global_load_dwordx4 v[28:31], v[88:89], off offset:320
	global_load_dwordx4 v[32:35], v[12:13], off offset:256
	global_load_dwordx4 v[36:39], v[12:13], off offset:320
	global_load_dwordx4 v[40:43], v[90:91], off offset:256
	global_load_dwordx4 v[44:47], v[90:91], off offset:320
	global_load_dwordx4 v[48:51], v[92:93], off offset:256
	global_load_dwordx4 v[52:55], v[92:93], off offset:320
	global_load_dwordx4 v[56:59], v[100:101], off offset:256
	global_load_dwordx4 v[60:63], v[100:101], off offset:320
	global_load_dwordx4 v[64:67], v[88:89], off offset:384
	global_load_dwordx4 v[68:71], v[88:89], off offset:448
	global_load_dwordx4 v[72:75], v[12:13], off offset:384
	global_load_dwordx4 v[76:79], v[12:13], off offset:448
	global_load_dwordx4 v[80:83], v[90:91], off offset:384
	global_load_dwordx4 v[84:87], v[90:91], off offset:448
	s_nop 0
	global_load_dwordx4 v[88:91], v[92:93], off offset:384
	s_nop 0
	global_load_dwordx4 v[92:95], v[92:93], off offset:448
	s_nop 0
	global_load_dwordx4 v[96:99], v[100:101], off offset:384
	s_nop 0
	global_load_dwordx4 v[100:103], v[100:101], off offset:448
	s_waitcnt vmcnt(17)
	v_mfma_f32_16x16x32_bf16 v[8:11], v[24:27], v[32:35], v[8:11]
	s_waitcnt vmcnt(15)
	v_mfma_f32_16x16x32_bf16 v[16:19], v[24:27], v[40:43], v[16:19]
	s_waitcnt vmcnt(13)
	v_mfma_f32_16x16x32_bf16 v[20:23], v[24:27], v[48:51], v[20:23]
	s_waitcnt vmcnt(11)
	v_mfma_f32_16x16x32_bf16 v[4:7], v[24:27], v[56:59], v[4:7]
	v_mfma_f32_16x16x32_bf16 v[8:11], v[28:31], v[36:39], v[8:11]
	v_mfma_f32_16x16x32_bf16 v[16:19], v[28:31], v[44:47], v[16:19]
	v_mfma_f32_16x16x32_bf16 v[20:23], v[28:31], v[52:55], v[20:23]
	s_waitcnt vmcnt(10)
	v_mfma_f32_16x16x32_bf16 v[4:7], v[28:31], v[60:63], v[4:7]
	s_waitcnt vmcnt(7)
	v_mfma_f32_16x16x32_bf16 v[8:11], v[64:67], v[72:75], v[8:11]
	s_waitcnt vmcnt(5)
	v_mfma_f32_16x16x32_bf16 v[16:19], v[64:67], v[80:83], v[16:19]
	s_waitcnt vmcnt(3)
	v_mfma_f32_16x16x32_bf16 v[20:23], v[64:67], v[88:91], v[20:23]
	s_waitcnt vmcnt(1)
	v_mfma_f32_16x16x32_bf16 v[4:7], v[64:67], v[96:99], v[4:7]
	v_mfma_f32_16x16x32_bf16 v[8:11], v[68:71], v[76:79], v[8:11]
	v_mfma_f32_16x16x32_bf16 v[16:19], v[68:71], v[84:87], v[16:19]
	v_mfma_f32_16x16x32_bf16 v[20:23], v[68:71], v[92:95], v[20:23]
	s_waitcnt vmcnt(0)
	v_mfma_f32_16x16x32_bf16 v[4:7], v[68:71], v[100:103], v[4:7]
	s_nop 3
	ds_write_b128 v3, v[8:11]
	ds_write_b128 v3, v[16:19] offset:1024
	ds_write_b128 v3, v[20:23] offset:2048
	s_nop 0
	ds_write_b128 v3, v[4:7] offset:3072
	s_waitcnt lgkmcnt(0)
	s_barrier
; __device__ __forceinline__ unsigned pk2(float lo, float hi) { const f32x2_g v = {lo, hi}; return __builtin_bit_cast(unsigned, __builtin_convertvector(v, bf16x2_g)); }
; __device__ __forceinline__ float shflx(float v, int mask, int lane) { return __int_as_float(__builtin_amdgcn_ds_bpermute((lane ^ mask) << 2, __float_as_int(v))); }
; __global__ void __launch_bounds__(512, 2) mk_fwd(Args args) {
;     ...
;                 if (wave == 0) {
; #pragma unroll
;                     for (int nt = 0; nt < 4; ++nt) { f32x4 s = red[nt * 64 + lane];
; #pragma unroll
;                         for (int w = 1; w < 8; ++w) s += red[(w * 4 + nt) * 64 + lane];
;                         acc[nt] = s; }
; #pragma unroll
;                     for (int r = 0; r < 4; ++r) {
;                         const int t = r0 + 4 * l4 + r, j = t - 3 * TPB, sidx = j - CTXL, prow = sidx >> 6, pcol = sidx & 63;
; #pragma unroll
;                         for (int nt = 0; nt < 4; ++nt) {
;                             const float v = acc[nt][r], p = shflx(v, 1, lane);
;                             const float2 cs = TAB64[((nt >> 1) ? pcol : prow) * 16 + 8 * (nt & 1) + (l15 >> 1)];
;                             const float x1 = (l15 & 1) ? p : v, x2 = (l15 & 1) ? v : p;
;                             const float o1 = x1 * cs.x - x2 * cs.y, o2 = x2 * cs.x + x1 * cs.y;
;                             if (!(l15 & 1)) { const unsigned w = pk2(o1, o2);
; #pragma unroll
;                                 for (int h = 0; h < 8; ++h) *(unsigned*)(KM + (size_t)t * 1536 + h * 192 + 128 + 16 * nt + l15) = w; }
;                         }
	s_cbranch_scc1 .LBB0_559
	v_lshlrev_b32_e32 v2, 2, v2
	v_xor_b32_e32 v107, 4, v2
	v_and_b32_e32 v2, 1, v147
	v_cmp_eq_u32_e32 vcc, 0, v2
	ds_read_b128 v[2:5], v14
	ds_read_b128 v[6:9], v14 offset:4096
	ds_read_b128 v[10:13], v14 offset:8192
	ds_read_b128 v[82:85], v14 offset:1024
	ds_read_b128 v[86:89], v14 offset:5120
	v_readlane_b32 s1, v254, 22
	v_lshrrev_b32_e32 v109, 1, v159
	v_mov_b64_e32 v[98:99], s[16:17]
	s_waitcnt lgkmcnt(3)
	v_pk_add_f32 v[8:9], v[4:5], v[8:9]
	v_pk_add_f32 v[6:7], v[2:3], v[6:7]
	ds_read_b128 v[2:5], v14 offset:12288
	ds_read_b128 v[90:93], v14 offset:9216
	s_waitcnt lgkmcnt(4)
	v_pk_add_f32 v[12:13], v[8:9], v[12:13]
	v_pk_add_f32 v[10:11], v[6:7], v[10:11]
	ds_read_b128 v[6:9], v14 offset:16384
	ds_read_b128 v[94:97], v14 offset:13312
	s_waitcnt lgkmcnt(3)
	v_pk_add_f32 v[12:13], v[12:13], v[4:5]
	v_pk_add_f32 v[10:11], v[10:11], v[2:3]
	ds_read_b128 v[2:5], v14 offset:20480
	ds_read_b128 v[66:69], v14 offset:17408
	s_waitcnt lgkmcnt(3)
	v_pk_add_f32 v[12:13], v[12:13], v[8:9]
	v_pk_add_f32 v[10:11], v[10:11], v[6:7]
	ds_read_b128 v[6:9], v14 offset:24576
	ds_read_b128 v[70:73], v14 offset:21504
	s_waitcnt lgkmcnt(3)
	v_pk_add_f32 v[12:13], v[12:13], v[4:5]
	v_pk_add_f32 v[10:11], v[10:11], v[2:3]
	ds_read_b128 v[2:5], v14 offset:28672
	ds_read_b128 v[74:77], v14 offset:25600
	s_waitcnt lgkmcnt(3)
	v_pk_add_f32 v[8:9], v[12:13], v[8:9]
	v_pk_add_f32 v[6:7], v[10:11], v[6:7]
	ds_read_b128 v[78:81], v14 offset:29696
	s_waitcnt lgkmcnt(2)
	v_pk_add_f32 v[100:101], v[8:9], v[4:5]
	v_pk_add_f32 v[102:103], v[6:7], v[2:3]
	ds_read_b128 v[42:45], v14 offset:2048
	ds_read_b128 v[22:25], v14 offset:3072
	ds_read_b128 v[62:65], v14 offset:6144
	ds_read_b128 v[30:33], v14 offset:7168
	ds_read_b128 v[58:61], v14 offset:10240
	ds_read_b128 v[26:29], v14 offset:11264
	ds_read_b128 v[54:57], v14 offset:14336
	ds_read_b128 v[18:21], v14 offset:15360
	ds_read_b128 v[50:53], v14 offset:18432
	ds_read_b128 v[2:5], v14 offset:19456
	ds_read_b128 v[46:49], v14 offset:22528
	ds_read_b128 v[6:9], v14 offset:23552
	ds_read_b128 v[38:41], v14 offset:26624
	ds_read_b128 v[10:13], v14 offset:27648
	ds_read_b128 v[34:37], v14 offset:30720
	ds_read_b128 v[14:17], v14 offset:31744
	ds_bpermute_b32 v106, v107, v102
	v_or_b32_e32 v108, s1, v146
	v_readlane_b32 s1, v254, 33
	v_mad_i64_i32 v[104:105], s[4:5], v108, s47, v[98:99]
	s_nop 0
	v_or_b32_e32 v98, s1, v109
	v_ashrrev_i32_e32 v99, 31, v98
	v_lshlrev_b32_e32 v178, 1, v159
	v_lshlrev_b32_e32 v139, 3, v109
	v_and_b32_e32 v136, 60, v108
	v_lshl_or_b32 v136, v136, 7, v139
	v_or_b32_e32 v137, 1, v108
	v_and_b32_e32 v137, 61, v137
	v_lshl_or_b32 v137, v137, 7, v139
	v_or_b32_e32 v138, 2, v108
	v_and_b32_e32 v138, 62, v138
	v_lshl_or_b32 v138, v138, 7, v139
	v_or_b32_e32 v140, 3, v108
	v_and_b32_e32 v140, 63, v140
	v_lshl_or_b32 v140, v140, 7, v139
	v_lshl_add_u64 v[142:143], v[98:99], 3, s[12:13]
	global_load_dwordx2 v[116:117], v[142:143], off
	global_load_dwordx2 v[118:119], v[142:143], off offset:64
	global_load_dwordx2 v[120:121], v136, s[12:13]
	global_load_dwordx2 v[122:123], v136, s[12:13] offset:64
	global_load_dwordx2 v[124:125], v137, s[12:13]
	global_load_dwordx2 v[126:127], v137, s[12:13] offset:64
	global_load_dwordx2 v[128:129], v138, s[12:13]
	global_load_dwordx2 v[130:131], v138, s[12:13] offset:64
	global_load_dwordx2 v[132:133], v140, s[12:13]
	global_load_dwordx2 v[134:135], v140, s[12:13] offset:64
	s_waitcnt vmcnt(0)
	s_and_saveexec_b64 s[4:5], vcc
	s_cbranch_execz .LBB0_528
	v_lshl_add_u64 v[110:111], v[98:99], 3, s[12:13]
	v_mov_b64_e32 v[110:111], v[116:117]
	s_waitcnt lgkmcnt(0)
	v_pk_mul_f32 v[112:113], v[110:111], v[106:107] op_sel:[1,0] op_sel_hi:[0,0]
	v_pk_fma_f32 v[114:115], v[102:103], v[110:111], v[112:113] neg_lo:[0,0,1] neg_hi:[0,0,1]
	v_pk_fma_f32 v[110:111], v[102:103], v[110:111], v[112:113] op_sel_hi:[0,1,1]
	v_cvt_pk_bf16_f32 v106, v114, v111
	v_lshl_add_u64 v[110:111], v[104:105], 0, v[178:179]
	global_store_dword v[110:111], v106, off offset:256
	global_store_dword v[110:111], v106, off offset:640
	global_store_dword v[110:111], v106, off offset:1024
	global_store_dword v[110:111], v106, off offset:1408
	global_store_dword v[110:111], v106, off offset:1792
	global_store_dword v[110:111], v106, off offset:2176
	global_store_dword v[110:111], v106, off offset:2560
	global_store_dword v[110:111], v106, off offset:2944
.LBB0_528:
	s_or_b64 exec, exec, s[4:5]
	v_pk_add_f32 v[82:83], v[82:83], v[86:87]
	v_pk_add_f32 v[84:85], v[84:85], v[88:89]
	v_pk_add_f32 v[82:83], v[82:83], v[90:91]
	v_pk_add_f32 v[84:85], v[84:85], v[92:93]
	v_pk_add_f32 v[82:83], v[82:83], v[94:95]
	v_pk_add_f32 v[84:85], v[84:85], v[96:97]
	v_pk_add_f32 v[66:67], v[82:83], v[66:67]
	s_nop 0
	v_pk_add_f32 v[66:67], v[66:67], v[70:71]
	s_waitcnt lgkmcnt(14)
	v_pk_add_f32 v[66:67], v[66:67], v[74:75]
	s_nop 0
	v_pk_add_f32 v[70:71], v[66:67], v[78:79]
	ds_bpermute_b32 v74, v107, v70
	v_pk_add_f32 v[66:67], v[84:85], v[68:69]
	s_nop 0
	v_pk_add_f32 v[66:67], v[66:67], v[72:73]
	s_nop 0
	v_pk_add_f32 v[66:67], v[66:67], v[76:77]
	s_nop 0
	v_pk_add_f32 v[66:67], v[66:67], v[80:81]
	s_and_saveexec_b64 s[4:5], vcc
	s_cbranch_execz .LBB0_530
	v_lshl_add_u64 v[68:69], v[98:99], 3, s[12:13]
	v_mov_b64_e32 v[68:69], v[118:119]
	s_waitcnt lgkmcnt(0)
	v_pk_mul_f32 v[72:73], v[68:69], v[74:75] op_sel:[1,0] op_sel_hi:[0,0]
	v_pk_fma_f32 v[74:75], v[70:71], v[68:69], v[72:73] neg_lo:[0,0,1] neg_hi:[0,0,1]
	v_pk_fma_f32 v[68:69], v[70:71], v[68:69], v[72:73] op_sel_hi:[0,1,1]
	v_cvt_pk_bf16_f32 v72, v74, v69
	v_lshl_add_u64 v[68:69], v[104:105], 0, v[178:179]
	global_store_dword v[68:69], v72, off offset:288
	global_store_dword v[68:69], v72, off offset:672
	global_store_dword v[68:69], v72, off offset:1056
	global_store_dword v[68:69], v72, off offset:1440
	global_store_dword v[68:69], v72, off offset:1824
	global_store_dword v[68:69], v72, off offset:2208
	global_store_dword v[68:69], v72, off offset:2592
	global_store_dword v[68:69], v72, off offset:2976
; __device__ __forceinline__ unsigned pk2(float lo, float hi) { const f32x2_g v = {lo, hi}; return __builtin_bit_cast(unsigned, __builtin_convertvector(v, bf16x2_g)); }
; __device__ __forceinline__ float shflx(float v, int mask, int lane) { return __int_as_float(__builtin_amdgcn_ds_bpermute((lane ^ mask) << 2, __float_as_int(v))); }
; __global__ void __launch_bounds__(512, 2) mk_fwd(Args args) {
;     ...
;                     for (int r = 0; r < 4; ++r) {
;                         const int t = r0 + 4 * l4 + r, j = t - 3 * TPB, sidx = j - CTXL, prow = sidx >> 6, pcol = sidx & 63;
; #pragma unroll
;                         for (int nt = 0; nt < 4; ++nt) {
;                             const float v = acc[nt][r], p = shflx(v, 1, lane);
;                             const float2 cs = TAB64[((nt >> 1) ? pcol : prow) * 16 + 8 * (nt & 1) + (l15 >> 1)];
;                             const float x1 = (l15 & 1) ? p : v, x2 = (l15 & 1) ? v : p;
;                             const float o1 = x1 * cs.x - x2 * cs.y, o2 = x2 * cs.x + x1 * cs.y;
;                             if (!(l15 & 1)) { const unsigned w = pk2(o1, o2);
; #pragma unroll
;                                 for (int h = 0; h < 8; ++h) *(unsigned*)(KM + (size_t)t * 1536 + h * 192 + 128 + 16 * nt + l15) = w; }
;                         }
.LBB0_530:
	s_or_b64 exec, exec, s[4:5]
	v_pk_add_f32 v[42:43], v[42:43], v[62:63]
	v_pk_add_f32 v[44:45], v[44:45], v[64:65]
	s_waitcnt lgkmcnt(13)
	v_pk_add_f32 v[42:43], v[42:43], v[58:59]
	v_pk_add_f32 v[44:45], v[44:45], v[60:61]
	s_waitcnt lgkmcnt(11)
	v_pk_add_f32 v[42:43], v[42:43], v[54:55]
	v_pk_add_f32 v[44:45], v[44:45], v[56:57]
	s_waitcnt lgkmcnt(9)
	v_pk_add_f32 v[42:43], v[42:43], v[50:51]
	v_pk_add_f32 v[44:45], v[44:45], v[52:53]
	s_waitcnt lgkmcnt(7)
	v_pk_add_f32 v[42:43], v[42:43], v[46:47]
	v_pk_add_f32 v[44:45], v[44:45], v[48:49]
	s_waitcnt lgkmcnt(5)
	v_pk_add_f32 v[38:39], v[42:43], v[38:39]
	v_pk_add_f32 v[44:45], v[44:45], v[40:41]
	s_waitcnt lgkmcnt(3)
	v_pk_add_f32 v[38:39], v[38:39], v[34:35]
	ds_bpermute_b32 v40, v107, v38
	v_pk_add_f32 v[34:35], v[44:45], v[36:37]
	v_and_b32_e32 v37, 60, v108
	v_lshlrev_b32_e32 v36, 3, v109
	v_lshl_or_b32 v37, v37, 7, v36
	s_and_saveexec_b64 s[4:5], vcc
	s_cbranch_execz .LBB0_532
	v_mov_b64_e32 v[42:43], v[120:121]
	s_waitcnt lgkmcnt(0)
	v_pk_mul_f32 v[40:41], v[42:43], v[40:41] op_sel:[1,0] op_sel_hi:[0,0]
	v_pk_fma_f32 v[44:45], v[38:39], v[42:43], v[40:41] neg_lo:[0,0,1] neg_hi:[0,0,1]
	v_pk_fma_f32 v[40:41], v[38:39], v[42:43], v[40:41] op_sel_hi:[0,1,1]
	v_cvt_pk_bf16_f32 v42, v44, v41
	v_lshl_add_u64 v[40:41], v[104:105], 0, v[178:179]
	global_store_dword v[40:41], v42, off offset:320
	global_store_dword v[40:41], v42, off offset:704
	global_store_dword v[40:41], v42, off offset:1088
	global_store_dword v[40:41], v42, off offset:1472
	global_store_dword v[40:41], v42, off offset:1856
	global_store_dword v[40:41], v42, off offset:2240
	global_store_dword v[40:41], v42, off offset:2624
	global_store_dword v[40:41], v42, off offset:3008
.LBB0_532:
	s_or_b64 exec, exec, s[4:5]
	v_pk_add_f32 v[22:23], v[22:23], v[30:31]
	v_pk_add_f32 v[24:25], v[24:25], v[32:33]
	v_pk_add_f32 v[22:23], v[22:23], v[26:27]
	v_pk_add_f32 v[24:25], v[24:25], v[28:29]
	v_pk_add_f32 v[18:19], v[22:23], v[18:19]
	v_pk_add_f32 v[20:21], v[24:25], v[20:21]
	v_pk_add_f32 v[2:3], v[18:19], v[2:3]
	s_nop 0
	v_pk_add_f32 v[2:3], v[2:3], v[6:7]
	s_nop 0
	v_pk_add_f32 v[2:3], v[2:3], v[10:11]
	s_waitcnt lgkmcnt(3)
	v_pk_add_f32 v[6:7], v[2:3], v[14:15]
	ds_bpermute_b32 v10, v107, v6
	v_pk_add_f32 v[2:3], v[20:21], v[4:5]
	s_nop 0
	v_pk_add_f32 v[2:3], v[2:3], v[8:9]
	s_nop 0
	v_pk_add_f32 v[2:3], v[2:3], v[12:13]
	s_nop 0
	v_pk_add_f32 v[2:3], v[2:3], v[16:17]
	s_and_saveexec_b64 s[4:5], vcc
	s_cbranch_execz .LBB0_534
	v_mov_b64_e32 v[4:5], v[122:123]
	v_lshl_add_u64 v[8:9], v[104:105], 0, v[178:179]
	s_waitcnt lgkmcnt(0)
	v_pk_mul_f32 v[10:11], v[4:5], v[10:11] op_sel:[1,0] op_sel_hi:[0,0]
	v_pk_fma_f32 v[12:13], v[6:7], v[4:5], v[10:11] neg_lo:[0,0,1] neg_hi:[0,0,1]
	v_pk_fma_f32 v[4:5], v[6:7], v[4:5], v[10:11] op_sel_hi:[0,1,1]
	v_cvt_pk_bf16_f32 v4, v12, v5
	global_store_dword v[8:9], v4, off offset:352
	global_store_dword v[8:9], v4, off offset:736
	global_store_dword v[8:9], v4, off offset:1120
	global_store_dword v[8:9], v4, off offset:1504
	global_store_dword v[8:9], v4, off offset:1888
	global_store_dword v[8:9], v4, off offset:2272
	global_store_dword v[8:9], v4, off offset:2656
	global_store_dword v[8:9], v4, off offset:3040
.LBB0_534:
	s_or_b64 exec, exec, s[4:5]
	ds_bpermute_b32 v8, v107, v103
	v_or_b32_e32 v9, 1, v108
	v_mov_b64_e32 v[4:5], s[16:17]
	v_mad_i64_i32 v[4:5], s[4:5], v9, s47, v[4:5]
	s_and_saveexec_b64 s[4:5], vcc
	s_cbranch_execz .LBB0_536
	s_waitcnt lgkmcnt(1)
	v_lshl_add_u64 v[10:11], v[98:99], 3, s[12:13]
	v_mov_b64_e32 v[10:11], v[116:117]
	s_waitcnt lgkmcnt(0)
	v_pk_mul_f32 v[12:13], v[10:11], v[8:9] op_sel:[1,0] op_sel_hi:[0,0]
	v_pk_fma_f32 v[14:15], v[102:103], v[10:11], v[12:13] op_sel:[1,0,0] neg_lo:[0,0,1] neg_hi:[0,0,1]
	v_pk_fma_f32 v[10:11], v[102:103], v[10:11], v[12:13] op_sel:[1,0,0]
	s_nop 0
	v_cvt_pk_bf16_f32 v8, v14, v11
	v_lshl_add_u64 v[10:11], v[4:5], 0, v[178:179]
	global_store_dword v[10:11], v8, off offset:256
	global_store_dword v[10:11], v8, off offset:640
	global_store_dword v[10:11], v8, off offset:1024
	global_store_dword v[10:11], v8, off offset:1408
	global_store_dword v[10:11], v8, off offset:1792
	global_store_dword v[10:11], v8, off offset:2176
	global_store_dword v[10:11], v8, off offset:2560
	global_store_dword v[10:11], v8, off offset:2944
.LBB0_536:
	s_or_b64 exec, exec, s[4:5]
	s_waitcnt lgkmcnt(0)
	ds_bpermute_b32 v8, v107, v71
	s_and_saveexec_b64 s[4:5], vcc
	s_cbranch_execz .LBB0_538
	v_lshl_add_u64 v[10:11], v[98:99], 3, s[12:13]
	v_mov_b64_e32 v[10:11], v[118:119]
	s_waitcnt lgkmcnt(0)
	v_pk_mul_f32 v[12:13], v[10:11], v[8:9] op_sel:[1,0] op_sel_hi:[0,0]
	v_pk_fma_f32 v[14:15], v[70:71], v[10:11], v[12:13] op_sel:[1,0,0] neg_lo:[0,0,1] neg_hi:[0,0,1]
	v_pk_fma_f32 v[10:11], v[70:71], v[10:11], v[12:13] op_sel:[1,0,0]
	s_nop 0
	v_cvt_pk_bf16_f32 v8, v14, v11
	v_lshl_add_u64 v[10:11], v[4:5], 0, v[178:179]
	global_store_dword v[10:11], v8, off offset:288
	global_store_dword v[10:11], v8, off offset:672
	global_store_dword v[10:11], v8, off offset:1056
	global_store_dword v[10:11], v8, off offset:1440
	global_store_dword v[10:11], v8, off offset:1824
	global_store_dword v[10:11], v8, off offset:2208
	global_store_dword v[10:11], v8, off offset:2592
	global_store_dword v[10:11], v8, off offset:2976
; __device__ __forceinline__ unsigned pk2(float lo, float hi) { const f32x2_g v = {lo, hi}; return __builtin_bit_cast(unsigned, __builtin_convertvector(v, bf16x2_g)); }
; __device__ __forceinline__ float shflx(float v, int mask, int lane) { return __int_as_float(__builtin_amdgcn_ds_bpermute((lane ^ mask) << 2, __float_as_int(v))); }
; __global__ void __launch_bounds__(512, 2) mk_fwd(Args args) {
;     ...
;                     for (int r = 0; r < 4; ++r) {
;                         const int t = r0 + 4 * l4 + r, j = t - 3 * TPB, sidx = j - CTXL, prow = sidx >> 6, pcol = sidx & 63;
; #pragma unroll
;                         for (int nt = 0; nt < 4; ++nt) {
;                             const float v = acc[nt][r], p = shflx(v, 1, lane);
;                             const float2 cs = TAB64[((nt >> 1) ? pcol : prow) * 16 + 8 * (nt & 1) + (l15 >> 1)];
;                             const float x1 = (l15 & 1) ? p : v, x2 = (l15 & 1) ? v : p;
;                             const float o1 = x1 * cs.x - x2 * cs.y, o2 = x2 * cs.x + x1 * cs.y;
;                             if (!(l15 & 1)) { const unsigned w = pk2(o1, o2);
; #pragma unroll
;                                 for (int h = 0; h < 8; ++h) *(unsigned*)(KM + (size_t)t * 1536 + h * 192 + 128 + 16 * nt + l15) = w; }
;                         }
.LBB0_538:
	s_or_b64 exec, exec, s[4:5]
	s_waitcnt lgkmcnt(0)
	ds_bpermute_b32 v8, v107, v39
	v_and_b32_e32 v9, 61, v9
	v_lshl_or_b32 v9, v9, 7, v36
	s_and_saveexec_b64 s[4:5], vcc
	s_cbranch_execz .LBB0_540
	v_mov_b64_e32 v[10:11], v[124:125]
	s_waitcnt lgkmcnt(0)
	v_pk_mul_f32 v[12:13], v[10:11], v[8:9] op_sel:[1,0] op_sel_hi:[0,0]
	v_pk_fma_f32 v[14:15], v[38:39], v[10:11], v[12:13] op_sel:[1,0,0] neg_lo:[0,0,1] neg_hi:[0,0,1]
	v_pk_fma_f32 v[10:11], v[38:39], v[10:11], v[12:13] op_sel:[1,0,0]
	s_nop 0
	v_cvt_pk_bf16_f32 v8, v14, v11
	v_lshl_add_u64 v[10:11], v[4:5], 0, v[178:179]
	global_store_dword v[10:11], v8, off offset:320
	global_store_dword v[10:11], v8, off offset:704
	global_store_dword v[10:11], v8, off offset:1088
	global_store_dword v[10:11], v8, off offset:1472
	global_store_dword v[10:11], v8, off offset:1856
	global_store_dword v[10:11], v8, off offset:2240
	global_store_dword v[10:11], v8, off offset:2624
	global_store_dword v[10:11], v8, off offset:3008
.LBB0_540:
	s_or_b64 exec, exec, s[4:5]
	s_waitcnt lgkmcnt(0)
	ds_bpermute_b32 v8, v107, v7
	s_and_saveexec_b64 s[4:5], vcc
	s_cbranch_execz .LBB0_542
	v_mov_b64_e32 v[10:11], v[126:127]
	v_lshl_add_u64 v[4:5], v[4:5], 0, v[178:179]
	s_waitcnt lgkmcnt(0)
	v_pk_mul_f32 v[8:9], v[10:11], v[8:9] op_sel:[1,0] op_sel_hi:[0,0]
	v_pk_fma_f32 v[12:13], v[6:7], v[10:11], v[8:9] op_sel:[1,0,0] neg_lo:[0,0,1] neg_hi:[0,0,1]
	v_pk_fma_f32 v[6:7], v[6:7], v[10:11], v[8:9] op_sel:[1,0,0]
	s_nop 0
	v_cvt_pk_bf16_f32 v6, v12, v7
	global_store_dword v[4:5], v6, off offset:352
	global_store_dword v[4:5], v6, off offset:736
	global_store_dword v[4:5], v6, off offset:1120
	global_store_dword v[4:5], v6, off offset:1504
	global_store_dword v[4:5], v6, off offset:1888
	global_store_dword v[4:5], v6, off offset:2272
	global_store_dword v[4:5], v6, off offset:2656
	global_store_dword v[4:5], v6, off offset:3040
.LBB0_542:
	s_or_b64 exec, exec, s[4:5]
	ds_bpermute_b32 v6, v107, v100
	v_or_b32_e32 v7, 2, v108
	v_mov_b64_e32 v[4:5], s[16:17]
	v_mad_i64_i32 v[4:5], s[4:5], v7, s47, v[4:5]
	s_and_saveexec_b64 s[4:5], vcc
	s_cbranch_execz .LBB0_544
	s_waitcnt lgkmcnt(1)
	v_lshl_add_u64 v[8:9], v[98:99], 3, s[12:13]
	v_mov_b64_e32 v[8:9], v[116:117]
	s_waitcnt lgkmcnt(0)
	v_pk_mul_f32 v[10:11], v[8:9], v[6:7] op_sel:[1,0] op_sel_hi:[0,0]
	v_pk_fma_f32 v[12:13], v[100:101], v[8:9], v[10:11] neg_lo:[0,0,1] neg_hi:[0,0,1]
	v_pk_fma_f32 v[8:9], v[100:101], v[8:9], v[10:11] op_sel_hi:[0,1,1]
	v_cvt_pk_bf16_f32 v6, v12, v9
	v_lshl_add_u64 v[8:9], v[4:5], 0, v[178:179]
	global_store_dword v[8:9], v6, off offset:256
	global_store_dword v[8:9], v6, off offset:640
	global_store_dword v[8:9], v6, off offset:1024
	global_store_dword v[8:9], v6, off offset:1408
	global_store_dword v[8:9], v6, off offset:1792
	global_store_dword v[8:9], v6, off offset:2176
	global_store_dword v[8:9], v6, off offset:2560
	global_store_dword v[8:9], v6, off offset:2944
.LBB0_544:
	s_or_b64 exec, exec, s[4:5]
	s_waitcnt lgkmcnt(0)
	ds_bpermute_b32 v6, v107, v66
	s_and_saveexec_b64 s[4:5], vcc
	s_cbranch_execz .LBB0_546
	v_lshl_add_u64 v[8:9], v[98:99], 3, s[12:13]
	v_mov_b64_e32 v[8:9], v[118:119]
	s_waitcnt lgkmcnt(0)
	v_pk_mul_f32 v[10:11], v[8:9], v[6:7] op_sel:[1,0] op_sel_hi:[0,0]
	v_pk_fma_f32 v[12:13], v[66:67], v[8:9], v[10:11] neg_lo:[0,0,1] neg_hi:[0,0,1]
	v_pk_fma_f32 v[8:9], v[66:67], v[8:9], v[10:11] op_sel_hi:[0,1,1]
	v_cvt_pk_bf16_f32 v6, v12, v9
	v_lshl_add_u64 v[8:9], v[4:5], 0, v[178:179]
	global_store_dword v[8:9], v6, off offset:288
	global_store_dword v[8:9], v6, off offset:672
	global_store_dword v[8:9], v6, off offset:1056
	global_store_dword v[8:9], v6, off offset:1440
	global_store_dword v[8:9], v6, off offset:1824
	global_store_dword v[8:9], v6, off offset:2208
	global_store_dword v[8:9], v6, off offset:2592
	global_store_dword v[8:9], v6, off offset:2976
.LBB0_546:
	s_or_b64 exec, exec, s[4:5]
	s_waitcnt lgkmcnt(0)
	ds_bpermute_b32 v6, v107, v34
	v_and_b32_e32 v7, 62, v7
	v_lshl_or_b32 v7, v7, 7, v36
	s_and_saveexec_b64 s[4:5], vcc
	s_cbranch_execz .LBB0_548
	v_mov_b64_e32 v[8:9], v[128:129]
	s_waitcnt lgkmcnt(0)
	v_pk_mul_f32 v[10:11], v[8:9], v[6:7] op_sel:[1,0] op_sel_hi:[0,0]
	v_pk_fma_f32 v[12:13], v[34:35], v[8:9], v[10:11] neg_lo:[0,0,1] neg_hi:[0,0,1]
	v_pk_fma_f32 v[8:9], v[34:35], v[8:9], v[10:11] op_sel_hi:[0,1,1]
	v_cvt_pk_bf16_f32 v6, v12, v9
	v_lshl_add_u64 v[8:9], v[4:5], 0, v[178:179]
	global_store_dword v[8:9], v6, off offset:320
	global_store_dword v[8:9], v6, off offset:704
	global_store_dword v[8:9], v6, off offset:1088
	global_store_dword v[8:9], v6, off offset:1472
	global_store_dword v[8:9], v6, off offset:1856
	global_store_dword v[8:9], v6, off offset:2240
	global_store_dword v[8:9], v6, off offset:2624
	global_store_dword v[8:9], v6, off offset:3008
; __device__ __forceinline__ unsigned pk2(float lo, float hi) { const f32x2_g v = {lo, hi}; return __builtin_bit_cast(unsigned, __builtin_convertvector(v, bf16x2_g)); }
; __device__ __forceinline__ float shflx(float v, int mask, int lane) { return __int_as_float(__builtin_amdgcn_ds_bpermute((lane ^ mask) << 2, __float_as_int(v))); }
; __global__ void __launch_bounds__(512, 2) mk_fwd(Args args) {
;     ...
;                     for (int r = 0; r < 4; ++r) {
;                         const int t = r0 + 4 * l4 + r, j = t - 3 * TPB, sidx = j - CTXL, prow = sidx >> 6, pcol = sidx & 63;
; #pragma unroll
;                         for (int nt = 0; nt < 4; ++nt) {
;                             const float v = acc[nt][r], p = shflx(v, 1, lane);
;                             const float2 cs = TAB64[((nt >> 1) ? pcol : prow) * 16 + 8 * (nt & 1) + (l15 >> 1)];
;                             const float x1 = (l15 & 1) ? p : v, x2 = (l15 & 1) ? v : p;
;                             const float o1 = x1 * cs.x - x2 * cs.y, o2 = x2 * cs.x + x1 * cs.y;
;                             if (!(l15 & 1)) { const unsigned w = pk2(o1, o2);
; #pragma unroll
;                                 for (int h = 0; h < 8; ++h) *(unsigned*)(KM + (size_t)t * 1536 + h * 192 + 128 + 16 * nt + l15) = w; }
;                         }
.LBB0_548:
	s_or_b64 exec, exec, s[4:5]
	s_waitcnt lgkmcnt(0)
	ds_bpermute_b32 v6, v107, v2
	s_and_saveexec_b64 s[4:5], vcc
	s_cbranch_execz .LBB0_550
	v_mov_b64_e32 v[8:9], v[130:131]
	v_lshl_add_u64 v[4:5], v[4:5], 0, v[178:179]
	s_waitcnt lgkmcnt(0)
	v_pk_mul_f32 v[6:7], v[8:9], v[6:7] op_sel:[1,0] op_sel_hi:[0,0]
	v_pk_fma_f32 v[10:11], v[2:3], v[8:9], v[6:7] neg_lo:[0,0,1] neg_hi:[0,0,1]
	v_pk_fma_f32 v[6:7], v[2:3], v[8:9], v[6:7] op_sel_hi:[0,1,1]
	v_cvt_pk_bf16_f32 v2, v10, v7
	global_store_dword v[4:5], v2, off offset:352
	global_store_dword v[4:5], v2, off offset:736
	global_store_dword v[4:5], v2, off offset:1120
	global_store_dword v[4:5], v2, off offset:1504
	global_store_dword v[4:5], v2, off offset:1888
	global_store_dword v[4:5], v2, off offset:2272
	global_store_dword v[4:5], v2, off offset:2656
	global_store_dword v[4:5], v2, off offset:3040
.LBB0_550:
	s_or_b64 exec, exec, s[4:5]
	ds_bpermute_b32 v2, v107, v101
	s_waitcnt lgkmcnt(1)
	v_or_b32_e32 v6, 3, v108
	v_mov_b64_e32 v[4:5], s[16:17]
	v_mad_i64_i32 v[4:5], s[4:5], v6, s47, v[4:5]
	s_and_saveexec_b64 s[4:5], vcc
	s_cbranch_execz .LBB0_552
	v_lshl_add_u64 v[8:9], v[98:99], 3, s[12:13]
	v_mov_b64_e32 v[8:9], v[116:117]
	v_mov_b32_e32 v10, v101
	s_waitcnt lgkmcnt(0)
	v_pk_mul_f32 v[12:13], v[8:9], v[2:3] op_sel:[1,0] op_sel_hi:[0,0]
	v_pk_fma_f32 v[14:15], v[10:11], v[8:9], v[12:13] op_sel_hi:[0,1,1] neg_lo:[0,0,1] neg_hi:[0,0,1]
	v_pk_fma_f32 v[8:9], v[10:11], v[8:9], v[12:13] op_sel_hi:[0,1,1]
	v_cvt_pk_bf16_f32 v2, v14, v9
	v_lshl_add_u64 v[8:9], v[4:5], 0, v[178:179]
	global_store_dword v[8:9], v2, off offset:256
	global_store_dword v[8:9], v2, off offset:640
	global_store_dword v[8:9], v2, off offset:1024
	global_store_dword v[8:9], v2, off offset:1408
	global_store_dword v[8:9], v2, off offset:1792
	global_store_dword v[8:9], v2, off offset:2176
	global_store_dword v[8:9], v2, off offset:2560
	global_store_dword v[8:9], v2, off offset:2944
.LBB0_552:
	s_or_b64 exec, exec, s[4:5]
	s_waitcnt lgkmcnt(0)
	ds_bpermute_b32 v2, v107, v67
	s_and_saveexec_b64 s[4:5], vcc
	s_cbranch_execz .LBB0_554
	v_lshl_add_u64 v[8:9], v[98:99], 3, s[12:13]
	v_mov_b64_e32 v[8:9], v[118:119]
	v_mov_b32_e32 v10, v67
	s_waitcnt lgkmcnt(0)
	v_pk_mul_f32 v[12:13], v[8:9], v[2:3] op_sel:[1,0] op_sel_hi:[0,0]
	v_pk_fma_f32 v[14:15], v[10:11], v[8:9], v[12:13] op_sel_hi:[0,1,1] neg_lo:[0,0,1] neg_hi:[0,0,1]
	v_pk_fma_f32 v[8:9], v[10:11], v[8:9], v[12:13] op_sel_hi:[0,1,1]
	v_cvt_pk_bf16_f32 v2, v14, v9
	v_lshl_add_u64 v[8:9], v[4:5], 0, v[178:179]
	global_store_dword v[8:9], v2, off offset:288
	global_store_dword v[8:9], v2, off offset:672
	global_store_dword v[8:9], v2, off offset:1056
	global_store_dword v[8:9], v2, off offset:1440
	global_store_dword v[8:9], v2, off offset:1824
	global_store_dword v[8:9], v2, off offset:2208
	global_store_dword v[8:9], v2, off offset:2592
	global_store_dword v[8:9], v2, off offset:2976
.LBB0_554:
	s_or_b64 exec, exec, s[4:5]
	s_waitcnt lgkmcnt(0)
	ds_bpermute_b32 v2, v107, v35
	v_and_b32_e32 v6, 63, v6
	v_lshl_or_b32 v6, v6, 7, v36
	s_and_saveexec_b64 s[4:5], vcc
	s_cbranch_execz .LBB0_556
	v_mov_b64_e32 v[8:9], v[132:133]
	v_mov_b32_e32 v10, v35
	s_waitcnt lgkmcnt(0)
	v_pk_mul_f32 v[12:13], v[8:9], v[2:3] op_sel:[1,0] op_sel_hi:[0,0]
	v_pk_fma_f32 v[14:15], v[10:11], v[8:9], v[12:13] op_sel_hi:[0,1,1] neg_lo:[0,0,1] neg_hi:[0,0,1]
	v_pk_fma_f32 v[8:9], v[10:11], v[8:9], v[12:13] op_sel_hi:[0,1,1]
	v_cvt_pk_bf16_f32 v2, v14, v9
	v_lshl_add_u64 v[8:9], v[4:5], 0, v[178:179]
	global_store_dword v[8:9], v2, off offset:320
	global_store_dword v[8:9], v2, off offset:704
	global_store_dword v[8:9], v2, off offset:1088
	global_store_dword v[8:9], v2, off offset:1472
	global_store_dword v[8:9], v2, off offset:1856
	global_store_dword v[8:9], v2, off offset:2240
	global_store_dword v[8:9], v2, off offset:2624
	global_store_dword v[8:9], v2, off offset:3008
.LBB0_556:
	s_or_b64 exec, exec, s[4:5]
	s_waitcnt lgkmcnt(0)
	ds_bpermute_b32 v2, v107, v3
	s_and_saveexec_b64 s[4:5], vcc
	s_cbranch_execz .LBB0_558
	v_mov_b64_e32 v[6:7], v[134:135]
	v_mov_b32_e32 v8, v3
	s_waitcnt lgkmcnt(0)
	v_pk_mul_f32 v[2:3], v[6:7], v[2:3] op_sel:[1,0] op_sel_hi:[0,0]
	v_pk_fma_f32 v[10:11], v[8:9], v[6:7], v[2:3] op_sel_hi:[0,1,1] neg_lo:[0,0,1] neg_hi:[0,0,1]
	v_pk_fma_f32 v[2:3], v[8:9], v[6:7], v[2:3] op_sel_hi:[0,1,1]
	v_cvt_pk_bf16_f32 v6, v10, v3
	v_lshl_add_u64 v[2:3], v[4:5], 0, v[178:179]
	global_store_dword v[2:3], v6, off offset:352
	global_store_dword v[2:3], v6, off offset:736
	global_store_dword v[2:3], v6, off offset:1120
	global_store_dword v[2:3], v6, off offset:1504
	global_store_dword v[2:3], v6, off offset:1888
	global_store_dword v[2:3], v6, off offset:2272
	global_store_dword v[2:3], v6, off offset:2656
	global_store_dword v[2:3], v6, off offset:3040
